# nt (streaming) hint on single-use input loads: samp_hg state loads, samp_b K/V/conv cache loads, norm x rows
# speedup vs baseline: 1.0061x; 1.0033x over previous
.LBB0_555:
	v_readlane_b32 s2, v251, 39
	s_andn2_b64 vcc, exec, s[0:1]
	v_readlane_b32 s3, v251, 40
	s_cbranch_vccnz .LBB0_628
	s_cmp_gt_i32 s57, 0
	s_mov_b64 s[2:3], -1
	s_cbranch_scc0 .LBB0_565
	v_readfirstlane_b32 s10, v146
	v_readfirstlane_b32 s11, v147
	v_readfirstlane_b32 s0, v81
	s_ashr_i32 s1, s0, 31
	s_lshl_b64 s[2:3], s[0:1], 3
	s_add_u32 s4, s94, s2
	v_mov_b32_e32 v122, v80
	s_addc_u32 s5, s95, s3
	s_load_dwordx2 s[2:3], s[4:5], 0x18
	s_and_b32 s6, s10, 0x1ff
	s_or_b32 s6, s52, s6
	s_mov_b32 s7, s53
	v_ashrrev_i32_e32 v0, 2, v122
	s_lshl_b64 s[6:7], s[6:7], 16
	v_and_b32_e32 v0, 0xffffffe0, v0
	s_waitcnt lgkmcnt(0)
	s_add_u32 s2, s2, s6
	v_ashrrev_i32_e32 v1, 31, v0
	v_and_b32_e32 v69, 0x7f, v122
	s_addc_u32 s3, s3, s7
	v_lshlrev_b64 v[0:1], 9, v[0:1]
	v_lshl_add_u64 v[2:3], s[2:3], 0, v[0:1]
	v_lshlrev_b32_e32 v208, 2, v69
	v_lshl_add_u64 v[2:3], v[2:3], 0, v[208:209]
	s_movk_i32 s2, 0x1000
	v_add_co_u32_e32 v4, vcc, s2, v2
	global_load_dword v32, v[2:3], off nt
	global_load_dword v33, v[2:3], off offset:512 nt
	global_load_dword v34, v[2:3], off offset:1024 nt
	global_load_dword v35, v[2:3], off offset:1536 nt
	global_load_dword v36, v[2:3], off offset:2048 nt
	global_load_dword v37, v[2:3], off offset:2560 nt
	global_load_dword v38, v[2:3], off offset:3072 nt
	global_load_dword v39, v[2:3], off offset:3584 nt
	v_addc_co_u32_e32 v5, vcc, 0, v3, vcc
	v_add_co_u32_e32 v6, vcc, s70, v2
	v_readfirstlane_b32 s6, v122
	s_nop 0
	v_addc_co_u32_e32 v7, vcc, 0, v3, vcc
	v_add_co_u32_e32 v2, vcc, 0x3000, v2
	global_load_dword v48, v[6:7], off nt
	global_load_dword v49, v[6:7], off offset:512 nt
	global_load_dword v50, v[6:7], off offset:1024 nt
	global_load_dword v51, v[6:7], off offset:1536 nt
	global_load_dword v52, v[6:7], off offset:2048 nt
	global_load_dword v53, v[6:7], off offset:2560 nt
	global_load_dword v54, v[6:7], off offset:3072 nt
	global_load_dword v55, v[6:7], off offset:3584 nt
	v_addc_co_u32_e32 v3, vcc, 0, v3, vcc
	global_load_dword v41, v[4:5], off offset:512 nt
	global_load_dword v42, v[4:5], off offset:1024 nt
	global_load_dword v43, v[4:5], off offset:1536 nt
	global_load_dword v44, v[4:5], off offset:2048 nt
	global_load_dword v45, v[4:5], off offset:2560 nt
	global_load_dword v46, v[4:5], off offset:3072 nt
	global_load_dword v47, v[4:5], off offset:3584 nt
	global_load_dword v56, v[2:3], off nt
	global_load_dword v40, v[6:7], off offset:-4096 nt
	global_load_dword v57, v[2:3], off offset:512 nt
	global_load_dword v58, v[2:3], off offset:1024 nt
	global_load_dword v59, v[2:3], off offset:1536 nt
	global_load_dword v60, v[2:3], off offset:2048 nt
	global_load_dword v61, v[2:3], off offset:2560 nt
	global_load_dword v62, v[2:3], off offset:3072 nt
	global_load_dword v63, v[2:3], off offset:3584 nt
	s_cmpk_gt_i32 s10, 0x1ff
	s_cbranch_scc1 .LBB0_564
	s_load_dwordx2 s[8:9], s[4:5], 0x18
	s_load_dwordx2 s[14:15], s[4:5], 0x90
	v_readlane_b32 s16, v250, 60
	v_readlane_b32 s18, v250, 62
	v_readlane_b32 s19, v250, 63
	s_waitcnt lgkmcnt(0)
	v_lshl_add_u64 v[0:1], s[8:9], 0, v[0:1]
	v_readlane_b32 s8, v252, 5
	s_add_u32 s2, s18, s0
	v_lshl_add_u64 v[64:65], v[0:1], 0, v[208:209]
	v_ashrrev_i32_e32 v3, 7, v122
	v_or_b32_e32 v0, s8, v69
	v_mov_b32_e32 v1, v209
	s_addc_u32 s3, s19, s1
	s_lshl_b64 s[12:13], s[0:1], 2
	v_lshl_add_u64 v[66:67], v[0:1], 2, s[14:15]
	v_lshlrev_b32_e32 v0, 5, v3
	v_and_b32_e32 v1, 0xffffff80, v122
	v_readlane_b32 s17, v250, 61
	s_add_u32 s12, s16, s12
	v_add_u32_e32 v68, 0, v1
	v_ashrrev_i32_e32 v1, 31, v0
	s_addc_u32 s13, s17, s13
	v_lshlrev_b64 v[0:1], 9, v[0:1]
	v_readlane_b32 s9, v252, 6
	v_lshl_add_u64 v[0:1], s[12:13], 0, v[0:1]
	s_add_u32 s4, s2, 0xb200000
	v_lshl_add_u64 v[0:1], v[0:1], 0, v[208:209]
	s_mov_b64 s[8:9], 0x4bbc000
	s_movk_i32 s1, 0xff88
	s_addc_u32 s5, s3, 0
	v_lshl_add_u64 v[70:71], v[0:1], 0, s[8:9]
	v_mad_u64_u32 v[72:73], s[8:9], v3, s1, v[68:69]
	s_lshr_b32 s1, s6, 4
	s_and_b32 s1, s1, 4
	v_add_u32_e32 v82, 0, v208
	v_and_b32_e32 v2, 63, v122
	v_lshlrev_b32_e32 v4, 11, v3
	v_and_b32_e32 v0, 0x3fffff80, v122
	s_add_u32 s6, s2, 0xbe00200
	v_add_u32_e32 v83, 0x4000, v3
	s_waitcnt vmcnt(34)
	v_lshl_add_u32 v84, v122, 2, 0
	v_lshl_add_u32 v85, v0, 2, v82
	v_cmp_eq_u32_e64 s[36:37], 0, v2
	v_add_u32_e32 v73, s1, v72
	s_addc_u32 s7, s3, 0
	v_lshlrev_b32_e32 v208, 1, v69
	v_add_u32_e32 v86, v82, v4
	s_mov_b32 s9, s10
	s_branch .LBB0_560

.LBB0_562:
	s_ashr_i32 s8, s9, 2
	s_and_b32 s9, s9, -4
	v_add_u32_e32 v74, s9, v83
	v_mov_b64_e32 v[78:79], s[4:5]
	v_mad_i64_i32 v[78:79], s[14:15], v74, s89, v[78:79]
	s_lshl_b32 s54, s13, 1
	v_lshl_add_u64 v[78:79], v[78:79], 0, s[54:55]
	v_lshl_add_u64 v[78:79], v[78:79], 0, v[208:209]
	global_load_ushort v198, v[78:79], off offset:2048
	s_movk_i32 s13, 0x1000
	s_ashr_i32 s9, s8, 31
	s_lshl_b64 s[8:9], s[8:9], 2
	s_add_u32 s8, s8, s52
	s_addc_u32 s9, s9, s53
	s_or_b32 s8, s8, s12
	s_lshl_b64 s[8:9], s[8:9], 16
	global_load_ushort v199, v[78:79], off offset:1024
	global_load_ushort v200, v[78:79], off offset:3072
	v_add_co_u32_e32 v78, vcc, s13, v78
	s_nop 1
	v_addc_co_u32_e32 v79, vcc, 0, v79, vcc
	global_load_ushort v75, v[78:79], off
	global_load_dword v77, v[66:67], off
	s_cmpk_gt_i32 s1, 0x1ff
	s_cbranch_scc1 .Lshg_nopf
	s_movk_i32 s98, 0x1000
	v_add_co_u32_e32 v16, vcc, s98, v24
	global_load_dword v0, v[24:25], off nt
	global_load_dword v1, v[24:25], off offset:512 nt
	global_load_dword v2, v[24:25], off offset:1024 nt
	global_load_dword v3, v[24:25], off offset:1536 nt
	global_load_dword v4, v[24:25], off offset:2048 nt
	global_load_dword v5, v[24:25], off offset:2560 nt
	global_load_dword v6, v[24:25], off offset:3072 nt
	global_load_dword v7, v[24:25], off offset:3584 nt
	v_addc_co_u32_e32 v17, vcc, 0, v25, vcc
	v_add_co_u32_e32 v26, vcc, s70, v24
	s_movk_i32 s98, 0x3000
	s_nop 0
	v_addc_co_u32_e32 v27, vcc, 0, v25, vcc
	global_load_dword v8, v[26:27], off offset:-4096 nt
	global_load_dword v9, v[16:17], off offset:512 nt
	global_load_dword v10, v[16:17], off offset:1024 nt
	global_load_dword v11, v[16:17], off offset:1536 nt
	global_load_dword v12, v[16:17], off offset:2048 nt
	global_load_dword v13, v[16:17], off offset:2560 nt
	global_load_dword v14, v[16:17], off offset:3072 nt
	global_load_dword v15, v[16:17], off offset:3584 nt
	s_nop 0
	global_load_dword v16, v[26:27], off nt
	global_load_dword v17, v[26:27], off offset:512 nt
	global_load_dword v18, v[26:27], off offset:1024 nt
	global_load_dword v19, v[26:27], off offset:1536 nt
	global_load_dword v20, v[26:27], off offset:2048 nt
	global_load_dword v21, v[26:27], off offset:2560 nt
	global_load_dword v22, v[26:27], off offset:3072 nt
	global_load_dword v23, v[26:27], off offset:3584 nt
	v_add_co_u32_e32 v210, vcc, s98, v24
	s_nop 1
	v_addc_co_u32_e32 v211, vcc, 0, v25, vcc
	global_load_dword v24, v[210:211], off nt
	global_load_dword v25, v[210:211], off offset:512 nt
	global_load_dword v26, v[210:211], off offset:1024 nt
	global_load_dword v27, v[210:211], off offset:1536 nt
	global_load_dword v28, v[210:211], off offset:2048 nt
	global_load_dword v29, v[210:211], off offset:2560 nt
	global_load_dword v30, v[210:211], off offset:3072 nt
	global_load_dword v31, v[210:211], off offset:3584 nt
	s_waitcnt vmcnt(34)
	s_branch .Lshg_join

.LBB0_570:
	s_ashr_i32 s54, s87, 1
	s_ashr_i32 s34, s54, 31
	v_readlane_b32 s36, v252, 9
	v_readlane_b32 s37, v252, 10
	s_add_u32 s36, s36, s54
	s_addc_u32 s37, s37, s34
	s_mul_i32 s34, s37, 0x1e00
	s_mul_hi_u32 s35, s36, 0x1e00
	s_add_i32 s35, s35, s34
	s_mul_i32 s34, s36, 0x1e00
	s_lshl_b64 s[34:35], s[34:35], 2
	s_waitcnt lgkmcnt(0)
	s_add_u32 s38, s68, s34
	s_addc_u32 s39, s69, s35
	v_mov_b32_e32 v24, 0
	v_mov_b32_e32 v36, 0
	v_mov_b32_e32 v37, 0
	v_mov_b32_e32 v38, 0
	v_mov_b32_e32 v39, 0
	s_and_saveexec_b64 s[70:71], s[0:1]
	s_cbranch_execz .LBB0_572
	v_lshl_add_u64 v[0:1], v[54:55], 2, s[38:39]
	global_load_dwordx4 v[36:39], v[0:1], off nt
.LBB0_572:
	s_or_b64 exec, exec, s[70:71]
	v_mov_b32_e32 v25, 0
	v_mov_b32_e32 v26, 0
	v_mov_b32_e32 v27, 0
	s_and_saveexec_b64 s[70:71], s[2:3]
	s_cbranch_execz .LBB0_574
	v_lshl_add_u64 v[0:1], v[56:57], 2, s[38:39]
	global_load_dwordx4 v[24:27], v[0:1], off nt
.LBB0_574:
	s_or_b64 exec, exec, s[70:71]
	v_mov_b32_e32 v40, 0
	v_mov_b32_e32 v44, 0
	v_mov_b32_e32 v45, 0
	v_mov_b32_e32 v46, 0
	v_mov_b32_e32 v47, 0
	s_and_saveexec_b64 s[70:71], s[4:5]
	s_cbranch_execz .LBB0_576
	v_lshl_add_u64 v[0:1], v[58:59], 2, s[38:39]
	global_load_dwordx4 v[44:47], v[0:1], off nt
.LBB0_576:
	s_or_b64 exec, exec, s[70:71]
	v_mov_b32_e32 v41, 0
	v_mov_b32_e32 v42, 0
	v_mov_b32_e32 v43, 0
	s_and_saveexec_b64 s[70:71], s[6:7]
	s_cbranch_execz .LBB0_578
	v_lshl_add_u64 v[0:1], v[60:61], 2, s[38:39]
	global_load_dwordx4 v[40:43], v[0:1], off nt
.LBB0_578:
	s_or_b64 exec, exec, s[70:71]
	s_and_b32 s71, s87, 1
	s_lshl_b32 s54, s54, 2
	s_lshl_b32 s72, s71, 6
	s_lshl_b64 s[38:39], s[36:37], 16
	s_add_u32 s73, s42, s38
	s_addc_u32 s75, s43, s39
	s_add_i32 s88, s54, 0x4000
	s_add_u32 s38, s40, s38
	s_addc_u32 s39, s41, s39
	s_lshl_b32 s70, s71, 8
	s_add_u32 s38, s38, s70
	s_addc_u32 s39, s39, 0
	s_add_u32 s74, s73, s70
	s_addc_u32 s75, s75, 0
	v_lshl_add_u64 v[0:1], s[38:39], 0, v[208:209]
	v_lshl_add_u64 v[2:3], s[74:75], 0, v[208:209]
	v_lshl_add_u64 v[4:5], v[0:1], 0, v[136:137]
	v_add_u32_e32 v141, s88, v157
	v_mov_b64_e32 v[152:153], s[52:53]
	global_load_dwordx4 v[28:31], v[4:5], off offset:16 nt
	global_load_dwordx4 v[32:35], v[4:5], off nt
	v_lshl_add_u64 v[4:5], v[2:3], 0, v[136:137]
	v_mad_i64_i32 v[152:153], s[38:39], v141, s89, v[152:153]
	v_mov_b32_e32 v141, v209
	global_load_dwordx4 v[16:19], v[4:5], off offset:16 nt
	global_load_dwordx4 v[20:23], v[4:5], off nt
	v_lshl_add_u64 v[0:1], v[0:1], 0, v[138:139]
	v_lshl_add_u64 v[4:5], v[2:3], 0, v[138:139]
	v_lshl_add_u64 v[192:193], v[152:153], 0, v[140:141]
	v_add_u32_e32 v141, s54, v158
	global_load_dwordx4 v[8:11], v[0:1], off offset:16 nt
	global_load_dwordx4 v[12:15], v[0:1], off nt
	s_nop 0
	global_load_dwordx4 v[0:3], v[4:5], off offset:16 nt
	s_nop 0
	global_load_dwordx4 v[4:7], v[4:5], off nt
	v_mad_i64_i32 v[196:197], s[38:39], v141, s89, v[48:49]
	global_load_ushort v191, v[192:193], off
	global_load_ushort v194, v[192:193], off offset:512
	s_nop 0
	global_load_ushort v192, v[196:197], off
	global_load_ushort v193, v[196:197], off offset:512
	v_mov_b32_e32 v189, 0
	v_mov_b32_e32 v190, 0
	s_and_saveexec_b64 s[38:39], s[8:9]
	s_cbranch_execz .LBB0_580
	v_add_u32_e32 v141, s88, v159
	v_mov_b64_e32 v[196:197], s[52:53]
	v_mad_i64_i32 v[196:197], s[74:75], v141, s89, v[196:197]
	s_lshl_b32 s54, s72, 1
	v_lshl_add_u64 v[196:197], v[196:197], 0, s[54:55]
	v_mov_b32_e32 v145, v209
	v_lshl_add_u64 v[196:197], v[196:197], 0, v[144:145]
	v_add_co_u32_e32 v196, vcc, 0x1000, v196
	s_nop 1
	v_addc_co_u32_e32 v197, vcc, 0, v197, vcc
	global_load_ushort v190, v[196:197], off offset:1536
	global_load_ushort v189, v[196:197], off offset:1792

.LBB0_732:
	s_lshl_b64 s[2:3], s[2:3], 12
	s_waitcnt lgkmcnt(0)
	s_add_u32 s0, s0, s2
	v_lshlrev_b32_e32 v144, 2, v235
	s_addc_u32 s1, s1, s3
	v_lshlrev_b32_e32 v208, 2, v144
	global_load_dwordx4 v[204:207], v208, s[0:1] nt
	global_load_dwordx4 v[188:191], v208, s[0:1] offset:1024 nt
	global_load_dwordx4 v[180:183], v208, s[0:1] offset:2048 nt
	global_load_dwordx4 v[172:175], v208, s[0:1] offset:3072 nt
	v_readlane_b32 s2, v251, 30
	v_readlane_b32 s3, v251, 31
	s_andn2_b64 vcc, exec, s[2:3]
	s_nop 0
	v_cndmask_b32_e64 v144, 0, 1, s[2:3]
	v_cmp_ne_u32_e64 s[0:1], 1, v144
	s_cbranch_vccnz .LBB0_734
	s_add_i32 s3, s10, 0xffffc000
	s_lshr_b32 s3, s3, 2
	s_ashr_i32 s2, s10, 12
	s_add_i32 s3, s3, 4
	s_cmpk_lt_i32 s10, 0x4000
	s_cselect_b32 s2, s2, s3
	s_mul_hi_i32 s3, s2, 0x6000
	s_mulk_i32 s2, 0x6000
	s_add_u32 s2, s31, s2
	s_addc_u32 s3, s34, s3
	v_lshl_add_u64 v[64:65], s[2:3], 0, v[208:209]
	s_mov_b64 s[8:9], 0x1000
	s_waitcnt vmcnt(0)
	v_add_co_u32_e32 v74, vcc, 0x1000, v64
	v_lshl_add_u64 v[72:73], v[64:65], 0, s[8:9]
	s_nop 0
	v_addc_co_u32_e32 v75, vcc, 0, v65, vcc
	global_load_dwordx4 v[120:123], v208, s[2:3]
	global_load_dwordx4 v[124:127], v208, s[2:3] offset:1024
	global_load_dwordx4 v[68:71], v[72:73], off offset:1024
	global_load_dwordx4 v[64:67], v[72:73], off offset:2048
	global_load_dwordx4 v[80:83], v[74:75], off
	s_nop 0
	global_load_dwordx4 v[72:75], v[72:73], off offset:3072
	s_nop 0
	global_load_dwordx4 v[140:143], v208, s[2:3] offset:2048
	global_load_dwordx4 v[136:139], v208, s[2:3] offset:3072

.LBB0_741:
	s_lshl_b64 s[16:17], s[16:17], 12
	s_waitcnt lgkmcnt(0)
	s_add_u32 s14, s14, s16
	s_addc_u32 s15, s15, s17
	global_load_dwordx4 v[200:203], v208, s[14:15] nt
	global_load_dwordx4 v[184:187], v208, s[14:15] offset:1024 nt
	global_load_dwordx4 v[176:179], v208, s[14:15] offset:2048 nt
	global_load_dwordx4 v[164:167], v208, s[14:15] offset:3072 nt
	s_and_b64 vcc, exec, s[0:1]
	s_cbranch_vccnz .LBB0_743
	s_add_i32 s11, s12, 0xffffc000
	s_lshr_b32 s11, s11, 2
	s_ashr_i32 s9, s12, 12
	s_add_i32 s11, s11, 4
	s_cmpk_lt_i32 s12, 0x4000
	s_cselect_b32 s9, s9, s11
	s_mul_hi_i32 s11, s9, 0x6000
	s_mulk_i32 s9, 0x6000
	s_add_u32 s12, s31, s9
	s_addc_u32 s13, s34, s11
	s_waitcnt vmcnt(0)
	v_lshl_add_u64 v[48:49], s[12:13], 0, v[208:209]
	s_mov_b64 s[14:15], 0x1000
	v_add_co_u32_e32 v58, vcc, 0x1000, v48
	v_lshl_add_u64 v[56:57], v[48:49], 0, s[14:15]
	s_nop 0
	v_addc_co_u32_e32 v59, vcc, 0, v49, vcc
	global_load_dwordx4 v[104:107], v208, s[12:13]
	global_load_dwordx4 v[108:111], v208, s[12:13] offset:1024
	global_load_dwordx4 v[52:55], v[56:57], off offset:1024
	global_load_dwordx4 v[48:51], v[56:57], off offset:2048
	global_load_dwordx4 v[60:63], v[58:59], off
	s_nop 0
	global_load_dwordx4 v[56:59], v[56:57], off offset:3072
	s_nop 0
	global_load_dwordx4 v[132:135], v208, s[12:13] offset:2048
	global_load_dwordx4 v[128:131], v208, s[12:13] offset:3072

.LBB0_750:
	s_lshl_b64 s[22:23], s[22:23], 12
	s_waitcnt lgkmcnt(0)
	s_add_u32 s16, s16, s22
	s_addc_u32 s17, s17, s23
	global_load_dwordx4 v[196:199], v208, s[16:17] nt
	global_load_dwordx4 v[168:171], v208, s[16:17] offset:1024 nt
	global_load_dwordx4 v[160:163], v208, s[16:17] offset:2048 nt
	global_load_dwordx4 v[152:155], v208, s[16:17] offset:3072 nt
	s_and_b64 vcc, exec, s[0:1]
	s_cbranch_vccnz .LBB0_752
	s_add_i32 s11, s12, 0xffffc000
	s_lshr_b32 s11, s11, 2
	s_ashr_i32 s9, s12, 12
	s_add_i32 s11, s11, 4
	s_cmpk_lt_i32 s12, 0x4000
	s_cselect_b32 s9, s9, s11
	s_mul_hi_i32 s11, s9, 0x6000
	s_mulk_i32 s9, 0x6000
	s_add_u32 s12, s31, s9
	s_addc_u32 s13, s34, s11
	s_waitcnt vmcnt(0)
	v_lshl_add_u64 v[32:33], s[12:13], 0, v[208:209]
	s_mov_b64 s[16:17], 0x1000
	v_add_co_u32_e32 v42, vcc, 0x1000, v32
	v_lshl_add_u64 v[40:41], v[32:33], 0, s[16:17]
	s_nop 0
	v_addc_co_u32_e32 v43, vcc, 0, v33, vcc
	global_load_dwordx4 v[88:91], v208, s[12:13]
	global_load_dwordx4 v[92:95], v208, s[12:13] offset:1024
	global_load_dwordx4 v[36:39], v[40:41], off offset:1024
	global_load_dwordx4 v[32:35], v[40:41], off offset:2048
	global_load_dwordx4 v[44:47], v[42:43], off
	s_nop 0
	global_load_dwordx4 v[40:43], v[40:41], off offset:3072
	s_nop 0
	global_load_dwordx4 v[116:119], v208, s[12:13] offset:2048
	global_load_dwordx4 v[112:115], v208, s[12:13] offset:3072

.LBB0_759:
	s_lshl_b64 s[26:27], s[26:27], 12
	s_waitcnt lgkmcnt(0)
	s_add_u32 s2, s2, s26
	s_addc_u32 s3, s3, s27
	global_load_dwordx4 v[192:195], v208, s[2:3] nt
	global_load_dwordx4 v[156:159], v208, s[2:3] offset:1024 nt
	global_load_dwordx4 v[148:151], v208, s[2:3] offset:2048 nt
	global_load_dwordx4 v[144:147], v208, s[2:3] offset:3072 nt
	s_and_b64 vcc, exec, s[0:1]
	s_cbranch_vccnz .LBB0_761
	s_add_i32 s3, s22, 0xffffc000
	s_lshr_b32 s3, s3, 2
	s_ashr_i32 s2, s22, 12
	s_add_i32 s3, s3, 4
	s_cmpk_lt_i32 s22, 0x4000
	s_cselect_b32 s2, s2, s3
	s_mul_hi_i32 s3, s2, 0x6000
	s_mulk_i32 s2, 0x6000
	s_add_u32 s2, s31, s2
	s_addc_u32 s3, s34, s3
	v_lshl_add_u64 v[16:17], s[2:3], 0, v[208:209]
	s_mov_b64 s[22:23], 0x1000
	v_add_co_u32_e32 v26, vcc, 0x1000, v16
	v_lshl_add_u64 v[24:25], v[16:17], 0, s[22:23]
	s_nop 0
	v_addc_co_u32_e32 v27, vcc, 0, v17, vcc
	global_load_dwordx4 v[76:79], v208, s[2:3]
	global_load_dwordx4 v[84:87], v208, s[2:3] offset:1024
	global_load_dwordx4 v[20:23], v[24:25], off offset:1024
	global_load_dwordx4 v[16:19], v[24:25], off offset:2048
	global_load_dwordx4 v[28:31], v[26:27], off
	s_nop 0
	global_load_dwordx4 v[24:27], v[24:25], off offset:3072
	s_nop 0
	global_load_dwordx4 v[100:103], v208, s[2:3] offset:2048
	global_load_dwordx4 v[96:99], v208, s[2:3] offset:3072
